# diff-attention prompt loop: next-tile K/V loads issued right after the LDS stores of the current tile, before the second barrier of the step
# baseline (speedup 1.0000x reference)
.LBB0_1080:
	s_cmp_ge_u32 s29, s1
	s_barrier
	s_waitcnt vmcnt(7)
	ds_write_b128 v145, v[16:19]
	s_waitcnt vmcnt(6)
	ds_write_b64 v146, v[20:21] offset:33792
	ds_write_b64 v146, v[22:23] offset:33808
	s_waitcnt vmcnt(5)
	ds_write_b128 v145, v[24:27] offset:8448
	s_waitcnt vmcnt(4)
	ds_write_b64 v146, v[28:29] offset:44032
	ds_write_b64 v146, v[30:31] offset:44048
	s_waitcnt vmcnt(3)
	ds_write_b128 v145, v[32:35] offset:16896
	s_waitcnt vmcnt(2)
	ds_write_b64 v146, v[36:37] offset:54272
	ds_write_b64 v146, v[38:39] offset:54288
	s_waitcnt vmcnt(1)
	ds_write_b128 v145, v[40:43] offset:25344
	s_waitcnt vmcnt(0)
	ds_write_b64 v146, v[44:45] offset:64512
	ds_write_b64 v146, v[46:47] offset:64528
	s_cbranch_scc1 .Lda_noload
	v_lshl_add_u64 v[40:41], s[96:97], 0, v[136:137]
	v_add_co_u32_e32 v16, vcc, 0x11140000, v40
	v_lshl_add_u64 v[42:43], s[96:97], 0, v[132:133]
	s_nop 0
	v_addc_co_u32_e32 v17, vcc, 0, v41, vcc
	v_add_co_u32_e32 v20, vcc, 0xd000000, v42
	s_nop 1
	v_addc_co_u32_e32 v21, vcc, 0, v43, vcc
	v_add_co_u32_e32 v24, vcc, 0x11150000, v40
	global_load_dwordx4 v[16:19], v[16:17], off
	s_nop 0
	global_load_dwordx4 v[20:23], v[20:21], off offset:128
	v_addc_co_u32_e32 v25, vcc, 0, v41, vcc
	v_add_co_u32_e32 v28, vcc, 0xd040000, v42
	s_nop 1
	v_addc_co_u32_e32 v29, vcc, 0, v43, vcc
	v_add_co_u32_e32 v32, vcc, 0x11160000, v40
	global_load_dwordx4 v[24:27], v[24:25], off
	s_nop 0
	global_load_dwordx4 v[28:31], v[28:29], off offset:128
	v_addc_co_u32_e32 v33, vcc, 0, v41, vcc
	v_add_co_u32_e32 v36, vcc, 0xd080000, v42
	s_nop 1
	v_addc_co_u32_e32 v37, vcc, 0, v43, vcc
	v_add_co_u32_e32 v40, vcc, 0x11170000, v40
	global_load_dwordx4 v[32:35], v[32:33], off
	s_nop 0
	global_load_dwordx4 v[36:39], v[36:37], off offset:128
	v_addc_co_u32_e32 v41, vcc, 0, v41, vcc
	v_add_co_u32_e32 v44, vcc, 0xd0c0000, v42
	s_nop 1
	v_addc_co_u32_e32 v45, vcc, 0, v43, vcc
	global_load_dwordx4 v[40:43], v[40:41], off
	s_nop 0
	global_load_dwordx4 v[44:47], v[44:45], off offset:128
.Lda_noload:
	s_waitcnt lgkmcnt(0)
	s_barrier
	s_cbranch_scc1 .Lda_last
